# FFN-up: the half-populated sixth round shared by all 256 WGs (each WG pair splits a unit into its two 128-row blocks; idle wave half only stages)
# baseline (speedup 1.0000x reference)
; #define PG8_STAGE(bufoff, gbase, voff) do { _Pragma("unroll") for (int _i = 0; _i < 2; ++_i) \
;         __builtin_amdgcn_global_load_lds((const unsigned*)((const char*)(gbase) + (voff)[_i]), (LAS unsigned*)(lds + (bufoff) + ldsw + _i * 8192), 16, 0, 0); } while (0)
; #define PG8_LDA(dst, b, h) do { _Pragma("unroll") for (int m = 0; m < 4; ++m) _Pragma("unroll") for (int k = 0; k < 2; ++k) dst[m][k] = *(const LAS bf16x8*)(lds + PG8_SA(b, h) + aoff + m * 2048 + k * 1024); } while (0)
; #define PG8_LDB(dst, b, h) do { _Pragma("unroll") for (int n = 0; n < 2; ++n) _Pragma("unroll") for (int k = 0; k < 2; ++k) dst[n][k] = *(const LAS bf16x8*)(lds + PG8_SB(b, h) + boff + n * 2048 + k * 1024); } while (0)
; #define PG8_MMA(ai, bj, At, Bt) do { __builtin_amdgcn_s_setprio(1); _Pragma("unroll") for (int m = 0; m < 4; ++m) _Pragma("unroll") for (int n = 0; n < 2; ++n) _Pragma("unroll") for (int k = 0; k < 2; ++k) \
;         acc[ai][bj][m][n] = __builtin_amdgcn_mfma_f32_16x16x32_bf16(Bt[n][k], At[m][k], acc[ai][bj][m][n], 0, 0, 0); __builtin_amdgcn_s_setprio(0); } while (0)
; #define PG8_WAIT_L(n) asm volatile("s_waitcnt lgkmcnt(" #n ")" ::: "memory")
; #define PG8_BAR __builtin_amdgcn_s_barrier()
; #define PG8_SCHED __builtin_amdgcn_sched_barrier(0)
; template <class Epi, class Sched>
; __device__ __forceinline__ void gemm_phase(LAS unsigned char* lds, const int K, const Sched& S, const Epi& E) {
;     ...
;         const bool has_next = S.next(ui + 1, nxt);
;         const char* nA = has_next ? nxt.pa : cA; const char* nB = has_next ? nxt.pb : cB;
;         for (int t = 0; t < nt; t += 2) {
;             const bool last = (t == nt - 2);
;             const char* a1 = cA + (size_t)(t + 1) * kstep;
;             const char* a2 = last ? nA : cA + (size_t)(t + 2) * kstep; const char* b2 = last ? nB : cB + (size_t)(t + 2) * kstep;
;             const char* a3 = a2 + kstep; const char* b3 = b2 + kstep;
;             PG8_LDB(B0, 0, 0); PG8_SCHED; PG8_LDA(At, 0, 0); PG8_STAGE(PG8_SA(1, 1), a1 + hstepA, voffA);
;             PG8_WAIT_L(8); PG8_BAR; PG8_WAIT_L(0); PG8_MMA(0, 0, At, B0); PG8_BAR; PG8_SCHED;
;             PG8_LDB(B1, 0, 1); PG8_STAGE(PG8_SB(0, 0), b2, voffB);
;             PG8_BAR; PG8_WAIT_L(0); PG8_MMA(0, 1, At, B1); PG8_BAR;
.LBB0_797:
	s_add_i32 s83, s83, 1
	s_mul_i32 s11, s83, s3
	s_add_i32 s11, s11, s2
	s_and_b32 s98, s2, 0x80
	s_cmp_eq_u32 s83, 5
	s_cselect_b32 s98, s98, 0
	s_sub_i32 s11, s11, s98
	s_cmpk_gt_i32 s11, 0x57f
	s_cselect_b64 s[50:51], -1, 0
	s_and_b64 vcc, exec, s[50:51]
	s_cbranch_vccnz .LBB0_799
	s_ashr_i32 s33, s11, 31
	s_lshr_b32 s33, s33, 29
	s_add_i32 s33, s11, s33
	s_ashr_i32 s48, s33, 3
	s_and_b32 s33, s33, -8
	s_sub_i32 s11, s11, s33
	s_cmp_lt_i32 s11, 0
	s_cselect_b32 s33, s79, 0xb0
	s_mul_i32 s11, s11, s33
	s_add_i32 s11, s11, s48
	s_mul_hi_i32 s33, s11, 0x2e8ba2e9
	s_lshr_b32 s48, s33, 31
	s_ashr_i32 s33, s33, 5
	s_add_i32 s33, s33, s48
	s_lshl_b32 s48, s33, 3
	s_mulk_i32 s33, 0xb0
	s_sub_i32 s11, s11, s33
	s_bfe_u32 s33, s11, 0x3001c
	s_add_i32 s33, s11, s33
	s_sext_i32_i16 s49, s33
	s_and_b32 s33, s33, 0xfff8
	s_sub_i32 s11, s11, s33
	s_sext_i32_i16 s11, s11
	s_add_i32 s48, s48, s11
	s_lshr_b32 s52, s49, 3
	s_ashr_i32 s93, s49, 3
	s_ashr_i32 s49, s48, 31
	s_lshl_b64 s[54:55], s[48:49], 19
	s_add_u32 s62, s45, s54
	s_addc_u32 s63, s74, s55
	s_bfe_i64 s[52:53], s[52:53], 0x100000
	s_lshl_b64 s[52:53], s[52:53], 19
	s_add_u32 s64, s75, s52
	s_addc_u32 s65, s76, s53
.LBB0_799:
	s_lshr_b32 s98, s2, 7
	s_cmp_eq_u32 s98, s77
	s_cselect_b32 s99, 1, 0
	s_cmp_lg_u32 s83, 6
	s_cselect_b32 s99, 1, s99
	v_lshl_or_b32 v253, s10, 7, v157
	v_lshlrev_b32_e32 v253, 2, v253
	global_load_dwordx4 v[224:227], v253, s[22:23]
	global_load_dwordx4 v[228:231], v253, s[24:25]
	global_load_dwordx4 v[232:235], v253, s[26:27]
	global_load_dwordx4 v[236:239], v253, s[36:37]
	s_add_u32 s11, s68, 0x100
	s_addc_u32 s33, s69, 0
	s_mov_b32 s49, -2
	s_waitcnt lgkmcnt(0)
.Lpeel_p7:
	ds_read_b128 v[128:131], v158
	ds_read_b128 v[132:135], v158 offset:1024
	ds_read_b128 v[148:151], v158 offset:2048
	ds_read_b128 v[162:165], v158 offset:3072
	s_add_u32 s68, s12, 0x100
	s_addc_u32 s69, s13, 0
	s_cmp_eq_u32 s49, 12
	s_cselect_b32 s73, s63, s69
	s_cselect_b32 s72, s62, s68
	s_cselect_b32 s71, s65, s33
	s_cselect_b32 s70, s64, s11
	v_lshl_add_u64 v[200:201], s[12:13], 0, v[144:145]
	s_add_i32 m0, s67, 0xc000
	ds_read_b128 v[166:169], v159
	ds_read_b128 v[172:175], v159 offset:1024
	ds_read_b128 v[176:179], v159 offset:2048
	ds_read_b128 v[180:183], v159 offset:3072
	ds_read_b128 v[184:187], v159 offset:4096
	ds_read_b128 v[188:191], v159 offset:5120
	ds_read_b128 v[192:195], v159 offset:6144
	ds_read_b128 v[196:199], v159 offset:7168
	global_load_lds_dwordx4 v[200:201], off
	v_lshl_add_u64 v[200:201], s[12:13], 0, v[146:147]
	s_add_i32 m0, s67, 0xe000
	s_nop 0
	global_load_lds_dwordx4 v[200:201], off
	s_waitcnt lgkmcnt(8)
	s_barrier
	s_waitcnt lgkmcnt(0)
	s_setprio 1
	s_waitcnt lgkmcnt(0)
	s_cmp_eq_u32 s99, 0
	s_cbranch_scc1 .Lp7_skipmma_0
	v_mfma_f32_16x16x32_bf16 v[84:87], v[128:131], v[166:169], 0
	v_mfma_f32_16x16x32_bf16 v[76:79], v[148:151], v[166:169], 0
	v_mfma_f32_16x16x32_bf16 v[124:127], v[128:131], v[176:179], 0
	v_mfma_f32_16x16x32_bf16 v[72:75], v[148:151], v[176:179], 0
	v_mfma_f32_16x16x32_bf16 v[120:123], v[128:131], v[184:187], 0
	v_mfma_f32_16x16x32_bf16 v[96:99], v[148:151], v[184:187], 0
	v_mfma_f32_16x16x32_bf16 v[116:119], v[128:131], v[192:195], 0
	v_mfma_f32_16x16x32_bf16 v[92:95], v[148:151], v[192:195], 0
	v_mfma_f32_16x16x32_bf16 v[84:87], v[132:135], v[172:175], v[84:87]
	v_mfma_f32_16x16x32_bf16 v[76:79], v[162:165], v[172:175], v[76:79]
	v_mfma_f32_16x16x32_bf16 v[124:127], v[132:135], v[180:183], v[124:127]
	v_mfma_f32_16x16x32_bf16 v[72:75], v[162:165], v[180:183], v[72:75]
	v_mfma_f32_16x16x32_bf16 v[120:123], v[132:135], v[188:191], v[120:123]
	v_mfma_f32_16x16x32_bf16 v[96:99], v[162:165], v[188:191], v[96:99]
	v_mfma_f32_16x16x32_bf16 v[116:119], v[132:135], v[196:199], v[116:119]
	v_mfma_f32_16x16x32_bf16 v[92:95], v[162:165], v[196:199], v[92:95]
.Lp7_skipmma_0:
	s_setprio 0
	s_barrier
	s_add_i32 s12, s88, s78
	v_lshl_add_u64 v[216:217], s[70:71], 0, v[138:139]
	s_mov_b32 m0, s12
	ds_read_b128 v[200:203], v160
	ds_read_b128 v[204:207], v160 offset:1024
	ds_read_b128 v[208:211], v160 offset:2048
	ds_read_b128 v[212:215], v160 offset:3072
	global_load_lds_dwordx4 v[216:217], off
	v_lshl_add_u64 v[218:219], s[70:71], 0, v[142:143]
	s_add_i32 m0, s12, 0x2000
	s_nop 0
	global_load_lds_dwordx4 v[218:219], off
	s_barrier
	s_waitcnt lgkmcnt(0)
	s_setprio 1
	s_waitcnt lgkmcnt(0)
	s_cmp_eq_u32 s99, 0
	s_cbranch_scc1 .Lp7_skipmma_1
	v_mfma_f32_16x16x32_bf16 v[60:63], v[200:203], v[166:169], 0
	v_mfma_f32_16x16x32_bf16 v[16:19], v[208:211], v[166:169], 0
	v_mfma_f32_16x16x32_bf16 v[56:59], v[200:203], v[176:179], 0
	v_mfma_f32_16x16x32_bf16 v[12:15], v[208:211], v[176:179], 0
	v_mfma_f32_16x16x32_bf16 v[52:55], v[200:203], v[184:187], 0
	v_mfma_f32_16x16x32_bf16 v[28:31], v[208:211], v[184:187], 0
	v_mfma_f32_16x16x32_bf16 v[48:51], v[200:203], v[192:195], 0
	v_mfma_f32_16x16x32_bf16 v[24:27], v[208:211], v[192:195], 0
	v_mfma_f32_16x16x32_bf16 v[60:63], v[204:207], v[172:175], v[60:63]
	v_mfma_f32_16x16x32_bf16 v[16:19], v[212:215], v[172:175], v[16:19]
	v_mfma_f32_16x16x32_bf16 v[56:59], v[204:207], v[180:183], v[56:59]
	v_mfma_f32_16x16x32_bf16 v[12:15], v[212:215], v[180:183], v[12:15]
	v_mfma_f32_16x16x32_bf16 v[52:55], v[204:207], v[188:191], v[52:55]
	v_mfma_f32_16x16x32_bf16 v[28:31], v[212:215], v[188:191], v[28:31]
	v_mfma_f32_16x16x32_bf16 v[48:51], v[204:207], v[196:199], v[48:51]
	v_mfma_f32_16x16x32_bf16 v[24:27], v[212:215], v[196:199], v[24:27]
; #define PG8_STAGE(bufoff, gbase, voff) do { _Pragma("unroll") for (int _i = 0; _i < 2; ++_i) \
;         __builtin_amdgcn_global_load_lds((const unsigned*)((const char*)(gbase) + (voff)[_i]), (LAS unsigned*)(lds + (bufoff) + ldsw + _i * 8192), 16, 0, 0); } while (0)
; #define PG8_LDA(dst, b, h) do { _Pragma("unroll") for (int m = 0; m < 4; ++m) _Pragma("unroll") for (int k = 0; k < 2; ++k) dst[m][k] = *(const LAS bf16x8*)(lds + PG8_SA(b, h) + aoff + m * 2048 + k * 1024); } while (0)
; #define PG8_LDB(dst, b, h) do { _Pragma("unroll") for (int n = 0; n < 2; ++n) _Pragma("unroll") for (int k = 0; k < 2; ++k) dst[n][k] = *(const LAS bf16x8*)(lds + PG8_SB(b, h) + boff + n * 2048 + k * 1024); } while (0)
; #define PG8_MMA(ai, bj, At, Bt) do { __builtin_amdgcn_s_setprio(1); _Pragma("unroll") for (int m = 0; m < 4; ++m) _Pragma("unroll") for (int n = 0; n < 2; ++n) _Pragma("unroll") for (int k = 0; k < 2; ++k) \
;         acc[ai][bj][m][n] = __builtin_amdgcn_mfma_f32_16x16x32_bf16(Bt[n][k], At[m][k], acc[ai][bj][m][n], 0, 0, 0); __builtin_amdgcn_s_setprio(0); } while (0)
; #define PG8_WAIT_V(n) asm volatile("s_waitcnt vmcnt(" #n ")" ::: "memory")
; #define PG8_WAIT_L(n) asm volatile("s_waitcnt lgkmcnt(" #n ")" ::: "memory")
; #define PG8_BAR __builtin_amdgcn_s_barrier()
; #define PG8_SCHED __builtin_amdgcn_sched_barrier(0)
; template <class Epi, class Sched>
; __device__ __forceinline__ void gemm_phase(LAS unsigned char* lds, const int K, const Sched& S, const Epi& E) {
;     ...
;             PG8_LDB(B1, 0, 1); PG8_STAGE(PG8_SB(0, 0), b2, voffB);
;             PG8_BAR; PG8_WAIT_L(0); PG8_MMA(0, 1, At, B1); PG8_BAR;
;             PG8_LDA(At, 0, 1); PG8_STAGE(PG8_SA(0, 0), a2, voffA);
;             PG8_BAR; PG8_WAIT_L(0); PG8_MMA(1, 0, At, B0); PG8_BAR; PG8_SCHED;
;             PG8_STAGE(PG8_SB(0, 1), b2 + hstep, voffB);
;             PG8_WAIT_V(6); PG8_BAR; PG8_MMA(1, 1, At, B1); PG8_BAR;
;             PG8_LDB(B0, 1, 0); PG8_SCHED; PG8_LDA(At, 1, 0); PG8_STAGE(PG8_SA(0, 1), a2 + hstepA, voffA);
;             PG8_WAIT_L(8); PG8_BAR; PG8_WAIT_L(0); PG8_MMA(0, 0, At, B0); PG8_BAR; PG8_SCHED;
.Lp7_skipmma_1:
	s_setprio 0
	s_mov_b32 m0, s67
	v_lshl_add_u64 v[220:221], s[72:73], 0, v[136:137]
	s_barrier
	ds_read_b128 v[166:169], v159 offset:16384
	ds_read_b128 v[172:175], v159 offset:17408
	ds_read_b128 v[176:179], v159 offset:18432
	ds_read_b128 v[180:183], v159 offset:19456
	ds_read_b128 v[184:187], v159 offset:20480
	ds_read_b128 v[188:191], v159 offset:21504
	ds_read_b128 v[192:195], v159 offset:22528
	ds_read_b128 v[196:199], v159 offset:23552
	global_load_lds_dwordx4 v[220:221], off
	v_lshl_add_u64 v[222:223], s[72:73], 0, v[140:141]
	s_mov_b32 m0, s80
	s_nop 0
	global_load_lds_dwordx4 v[222:223], off
	s_barrier
	s_waitcnt lgkmcnt(0)
	s_setprio 1
	s_waitcnt lgkmcnt(0)
	s_cmp_eq_u32 s99, 0
	s_cbranch_scc1 .Lp7_skipmma_2
	v_mfma_f32_16x16x32_bf16 v[112:115], v[128:131], v[166:169], 0
	v_mfma_f32_16x16x32_bf16 v[88:91], v[148:151], v[166:169], 0
	v_mfma_f32_16x16x32_bf16 v[104:107], v[128:131], v[176:179], 0
	v_mfma_f32_16x16x32_bf16 v[80:83], v[148:151], v[176:179], 0
	v_mfma_f32_16x16x32_bf16 v[100:103], v[128:131], v[184:187], 0
	v_mfma_f32_16x16x32_bf16 v[64:67], v[148:151], v[184:187], 0
	v_mfma_f32_16x16x32_bf16 v[108:111], v[128:131], v[192:195], 0
	v_mfma_f32_16x16x32_bf16 v[68:71], v[148:151], v[192:195], 0
	v_mfma_f32_16x16x32_bf16 v[112:115], v[132:135], v[172:175], v[112:115]
	v_mfma_f32_16x16x32_bf16 v[88:91], v[162:165], v[172:175], v[88:91]
	v_mfma_f32_16x16x32_bf16 v[104:107], v[132:135], v[180:183], v[104:107]
	v_mfma_f32_16x16x32_bf16 v[80:83], v[162:165], v[180:183], v[80:83]
	v_mfma_f32_16x16x32_bf16 v[100:103], v[132:135], v[188:191], v[100:103]
	v_mfma_f32_16x16x32_bf16 v[64:67], v[162:165], v[188:191], v[64:67]
	v_mfma_f32_16x16x32_bf16 v[108:111], v[132:135], v[196:199], v[108:111]
	v_mfma_f32_16x16x32_bf16 v[68:71], v[162:165], v[196:199], v[68:71]
.Lp7_skipmma_2:
	s_setprio 0
	s_barrier
	s_add_u32 s12, s70, 0x40000
	s_addc_u32 s13, s71, 0
	s_add_i32 s52, s89, s78
	v_lshl_add_u64 v[128:129], s[12:13], 0, v[138:139]
	s_mov_b32 m0, s52
	s_nop 0
	global_load_lds_dwordx4 v[128:129], off
	v_lshl_add_u64 v[128:129], s[12:13], 0, v[142:143]
	s_add_i32 m0, s52, 0x2000
	s_nop 0
	global_load_lds_dwordx4 v[128:129], off
	s_waitcnt vmcnt(6)
	s_barrier
	s_setprio 1
	s_cmp_eq_u32 s99, 0
	s_cbranch_scc1 .Lp7_skipmma_3
	v_mfma_f32_16x16x32_bf16 v[44:47], v[200:203], v[166:169], 0
	v_mfma_f32_16x16x32_bf16 v[20:23], v[208:211], v[166:169], 0
	v_mfma_f32_16x16x32_bf16 v[40:43], v[200:203], v[176:179], 0
	v_mfma_f32_16x16x32_bf16 v[8:11], v[208:211], v[176:179], 0
	v_mfma_f32_16x16x32_bf16 v[36:39], v[200:203], v[184:187], 0
	v_mfma_f32_16x16x32_bf16 v[0:3], v[208:211], v[184:187], 0
	v_mfma_f32_16x16x32_bf16 v[32:35], v[200:203], v[192:195], 0
	v_mfma_f32_16x16x32_bf16 v[4:7], v[208:211], v[192:195], 0
	v_mfma_f32_16x16x32_bf16 v[44:47], v[204:207], v[172:175], v[44:47]
	v_mfma_f32_16x16x32_bf16 v[20:23], v[212:215], v[172:175], v[20:23]
	v_mfma_f32_16x16x32_bf16 v[40:43], v[204:207], v[180:183], v[40:43]
	v_mfma_f32_16x16x32_bf16 v[8:11], v[212:215], v[180:183], v[8:11]
	v_mfma_f32_16x16x32_bf16 v[36:39], v[204:207], v[188:191], v[36:39]
	v_mfma_f32_16x16x32_bf16 v[0:3], v[212:215], v[188:191], v[0:3]
	v_mfma_f32_16x16x32_bf16 v[32:35], v[204:207], v[196:199], v[32:35]
	v_mfma_f32_16x16x32_bf16 v[4:7], v[212:215], v[196:199], v[4:7]
.Lp7_skipmma_3:
	s_setprio 0
	s_add_i32 s52, 0, 0x18000
	v_add_u32_e32 v161, s52, v156
	s_barrier
	ds_read_b128 v[128:131], v161
	ds_read_b128 v[132:135], v161 offset:1024
	ds_read_b128 v[148:151], v161 offset:2048
	ds_read_b128 v[162:165], v161 offset:3072
	s_add_u32 s12, s72, 0x20000
	s_addc_u32 s13, s73, 0
	s_mov_b32 m0, s81
	v_lshl_add_u64 v[200:201], s[12:13], 0, v[136:137]
	ds_read_b128 v[166:169], v159 offset:32768
	ds_read_b128 v[172:175], v159 offset:33792
	ds_read_b128 v[176:179], v159 offset:34816
	ds_read_b128 v[180:183], v159 offset:35840
	ds_read_b128 v[184:187], v159 offset:36864
	ds_read_b128 v[188:191], v159 offset:37888
	ds_read_b128 v[192:195], v159 offset:38912
	ds_read_b128 v[196:199], v159 offset:39936
	global_load_lds_dwordx4 v[200:201], off
	v_lshl_add_u64 v[200:201], s[12:13], 0, v[140:141]
	s_mov_b32 m0, s82
	s_nop 0
	global_load_lds_dwordx4 v[200:201], off
	s_waitcnt lgkmcnt(8)
	s_barrier
	s_waitcnt lgkmcnt(0)
	s_setprio 1
	s_waitcnt lgkmcnt(0)
	s_cmp_eq_u32 s99, 0
	s_cbranch_scc1 .Lp7_skipmma_4
	v_mfma_f32_16x16x32_bf16 v[84:87], v[128:131], v[166:169], v[84:87]
	v_mfma_f32_16x16x32_bf16 v[76:79], v[148:151], v[166:169], v[76:79]
	v_mfma_f32_16x16x32_bf16 v[124:127], v[128:131], v[176:179], v[124:127]
	v_mfma_f32_16x16x32_bf16 v[72:75], v[148:151], v[176:179], v[72:75]
	v_mfma_f32_16x16x32_bf16 v[120:123], v[128:131], v[184:187], v[120:123]
	v_mfma_f32_16x16x32_bf16 v[96:99], v[148:151], v[184:187], v[96:99]
	v_mfma_f32_16x16x32_bf16 v[116:119], v[128:131], v[192:195], v[116:119]
	v_mfma_f32_16x16x32_bf16 v[92:95], v[148:151], v[192:195], v[92:95]
	v_mfma_f32_16x16x32_bf16 v[84:87], v[132:135], v[172:175], v[84:87]
	v_mfma_f32_16x16x32_bf16 v[76:79], v[162:165], v[172:175], v[76:79]
	v_mfma_f32_16x16x32_bf16 v[124:127], v[132:135], v[180:183], v[124:127]
	v_mfma_f32_16x16x32_bf16 v[72:75], v[162:165], v[180:183], v[72:75]
	v_mfma_f32_16x16x32_bf16 v[120:123], v[132:135], v[188:191], v[120:123]
	v_mfma_f32_16x16x32_bf16 v[96:99], v[162:165], v[188:191], v[96:99]
	v_mfma_f32_16x16x32_bf16 v[116:119], v[132:135], v[196:199], v[116:119]
	v_mfma_f32_16x16x32_bf16 v[92:95], v[162:165], v[196:199], v[92:95]
; #define PG8_STAGE(bufoff, gbase, voff) do { _Pragma("unroll") for (int _i = 0; _i < 2; ++_i) \
;         __builtin_amdgcn_global_load_lds((const unsigned*)((const char*)(gbase) + (voff)[_i]), (LAS unsigned*)(lds + (bufoff) + ldsw + _i * 8192), 16, 0, 0); } while (0)
; #define PG8_LDA(dst, b, h) do { _Pragma("unroll") for (int m = 0; m < 4; ++m) _Pragma("unroll") for (int k = 0; k < 2; ++k) dst[m][k] = *(const LAS bf16x8*)(lds + PG8_SA(b, h) + aoff + m * 2048 + k * 1024); } while (0)
; #define PG8_LDB(dst, b, h) do { _Pragma("unroll") for (int n = 0; n < 2; ++n) _Pragma("unroll") for (int k = 0; k < 2; ++k) dst[n][k] = *(const LAS bf16x8*)(lds + PG8_SB(b, h) + boff + n * 2048 + k * 1024); } while (0)
; #define PG8_MMA(ai, bj, At, Bt) do { __builtin_amdgcn_s_setprio(1); _Pragma("unroll") for (int m = 0; m < 4; ++m) _Pragma("unroll") for (int n = 0; n < 2; ++n) _Pragma("unroll") for (int k = 0; k < 2; ++k) \
;         acc[ai][bj][m][n] = __builtin_amdgcn_mfma_f32_16x16x32_bf16(Bt[n][k], At[m][k], acc[ai][bj][m][n], 0, 0, 0); __builtin_amdgcn_s_setprio(0); } while (0)
; #define PG8_WAIT_V(n) asm volatile("s_waitcnt vmcnt(" #n ")" ::: "memory")
; #define PG8_WAIT_L(n) asm volatile("s_waitcnt lgkmcnt(" #n ")" ::: "memory")
; #define PG8_BAR __builtin_amdgcn_s_barrier()
; #define PG8_SCHED __builtin_amdgcn_sched_barrier(0)
; template <class Epi, class Sched>
; __device__ __forceinline__ void gemm_phase(LAS unsigned char* lds, const int K, const Sched& S, const Epi& E) {
;     ...
;             PG8_WAIT_L(8); PG8_BAR; PG8_WAIT_L(0); PG8_MMA(0, 0, At, B0); PG8_BAR; PG8_SCHED;
;             PG8_LDB(B1, 1, 1); PG8_STAGE(PG8_SB(1, 0), b3, voffB);
;             PG8_BAR; PG8_WAIT_L(0); PG8_MMA(0, 1, At, B1); PG8_BAR;
;             PG8_LDA(At, 1, 1); PG8_STAGE(PG8_SA(1, 0), a3, voffA);
;             PG8_BAR; PG8_WAIT_L(0); PG8_MMA(1, 0, At, B0); PG8_BAR; PG8_SCHED;
;             PG8_STAGE(PG8_SB(1, 1), b3 + hstep, voffB);
;             PG8_WAIT_V(6); PG8_BAR; PG8_MMA(1, 1, At, B1); PG8_BAR;
.Lp7_skipmma_4:
	s_setprio 0
	s_barrier
	s_add_i32 s53, 0, 0x1c000
	s_add_i32 s12, s52, s78
	v_add_u32_e32 v161, s53, v156
	v_lshl_add_u64 v[216:217], v[216:217], 0, s[38:39]
	s_mov_b32 m0, s12
	ds_read_b128 v[200:203], v161
	ds_read_b128 v[204:207], v161 offset:1024
	ds_read_b128 v[208:211], v161 offset:2048
	ds_read_b128 v[212:215], v161 offset:3072
	global_load_lds_dwordx4 v[216:217], off
	v_lshl_add_u64 v[216:217], v[218:219], 0, s[38:39]
	s_add_i32 m0, s12, 0x2000
	s_nop 0
	global_load_lds_dwordx4 v[216:217], off
	s_barrier
	s_waitcnt lgkmcnt(0)
	s_setprio 1
	s_waitcnt lgkmcnt(0)
	s_cmp_eq_u32 s99, 0
	s_cbranch_scc1 .Lp7_skipmma_5
	v_mfma_f32_16x16x32_bf16 v[60:63], v[200:203], v[166:169], v[60:63]
	v_mfma_f32_16x16x32_bf16 v[16:19], v[208:211], v[166:169], v[16:19]
	v_mfma_f32_16x16x32_bf16 v[56:59], v[200:203], v[176:179], v[56:59]
	v_mfma_f32_16x16x32_bf16 v[12:15], v[208:211], v[176:179], v[12:15]
	v_mfma_f32_16x16x32_bf16 v[52:55], v[200:203], v[184:187], v[52:55]
	v_mfma_f32_16x16x32_bf16 v[28:31], v[208:211], v[184:187], v[28:31]
	v_mfma_f32_16x16x32_bf16 v[48:51], v[200:203], v[192:195], v[48:51]
	v_mfma_f32_16x16x32_bf16 v[24:27], v[208:211], v[192:195], v[24:27]
	v_mfma_f32_16x16x32_bf16 v[60:63], v[204:207], v[172:175], v[60:63]
	v_mfma_f32_16x16x32_bf16 v[16:19], v[212:215], v[172:175], v[16:19]
	v_mfma_f32_16x16x32_bf16 v[56:59], v[204:207], v[180:183], v[56:59]
	v_mfma_f32_16x16x32_bf16 v[12:15], v[212:215], v[180:183], v[12:15]
	v_mfma_f32_16x16x32_bf16 v[52:55], v[204:207], v[188:191], v[52:55]
	v_mfma_f32_16x16x32_bf16 v[28:31], v[212:215], v[188:191], v[28:31]
	v_mfma_f32_16x16x32_bf16 v[48:51], v[204:207], v[196:199], v[48:51]
	v_mfma_f32_16x16x32_bf16 v[24:27], v[212:215], v[196:199], v[24:27]
.Lp7_skipmma_5:
	s_setprio 0
	s_mov_b32 m0, s84
	v_lshl_add_u64 v[216:217], v[220:221], 0, s[38:39]
	s_barrier
	ds_read_b128 v[166:169], v159 offset:49152
	ds_read_b128 v[172:175], v159 offset:50176
	ds_read_b128 v[176:179], v159 offset:51200
	ds_read_b128 v[180:183], v159 offset:52224
	ds_read_b128 v[184:187], v159 offset:53248
	ds_read_b128 v[188:191], v159 offset:54272
	ds_read_b128 v[192:195], v159 offset:55296
	ds_read_b128 v[196:199], v159 offset:56320
	global_load_lds_dwordx4 v[216:217], off
	v_lshl_add_u64 v[216:217], v[222:223], 0, s[38:39]
	s_mov_b32 m0, s85
	s_nop 0
	global_load_lds_dwordx4 v[216:217], off
	s_barrier
	s_waitcnt lgkmcnt(0)
	s_setprio 1
	s_waitcnt lgkmcnt(0)
	s_cmp_eq_u32 s99, 0
	s_cbranch_scc1 .Lp7_skipmma_6
	v_mfma_f32_16x16x32_bf16 v[112:115], v[128:131], v[166:169], v[112:115]
	v_mfma_f32_16x16x32_bf16 v[88:91], v[148:151], v[166:169], v[88:91]
	v_mfma_f32_16x16x32_bf16 v[104:107], v[128:131], v[176:179], v[104:107]
	v_mfma_f32_16x16x32_bf16 v[80:83], v[148:151], v[176:179], v[80:83]
	v_mfma_f32_16x16x32_bf16 v[100:103], v[128:131], v[184:187], v[100:103]
	v_mfma_f32_16x16x32_bf16 v[64:67], v[148:151], v[184:187], v[64:67]
	v_mfma_f32_16x16x32_bf16 v[108:111], v[128:131], v[192:195], v[108:111]
	v_mfma_f32_16x16x32_bf16 v[68:71], v[148:151], v[192:195], v[68:71]
	v_mfma_f32_16x16x32_bf16 v[112:115], v[132:135], v[172:175], v[112:115]
	v_mfma_f32_16x16x32_bf16 v[88:91], v[162:165], v[172:175], v[88:91]
	v_mfma_f32_16x16x32_bf16 v[104:107], v[132:135], v[180:183], v[104:107]
	v_mfma_f32_16x16x32_bf16 v[80:83], v[162:165], v[180:183], v[80:83]
	v_mfma_f32_16x16x32_bf16 v[100:103], v[132:135], v[188:191], v[100:103]
	v_mfma_f32_16x16x32_bf16 v[64:67], v[162:165], v[188:191], v[64:67]
	v_mfma_f32_16x16x32_bf16 v[108:111], v[132:135], v[196:199], v[108:111]
	v_mfma_f32_16x16x32_bf16 v[68:71], v[162:165], v[196:199], v[68:71]
.Lp7_skipmma_6:
	s_setprio 0
	s_barrier
	s_add_u32 s12, s70, 0x40080
	s_addc_u32 s13, s71, 0
	s_add_i32 s52, s53, s78
	v_lshl_add_u64 v[128:129], s[12:13], 0, v[138:139]
	s_mov_b32 m0, s52
	s_nop 0
	global_load_lds_dwordx4 v[128:129], off
	v_lshl_add_u64 v[128:129], s[12:13], 0, v[142:143]
	s_add_i32 m0, s52, 0x2000
	s_nop 0
	global_load_lds_dwordx4 v[128:129], off
	s_waitcnt vmcnt(6)
	s_barrier
	s_setprio 1
	s_cmp_eq_u32 s99, 0
	s_cbranch_scc1 .Lp7_skipmma_7
	v_mfma_f32_16x16x32_bf16 v[44:47], v[200:203], v[166:169], v[44:47]
	v_mfma_f32_16x16x32_bf16 v[20:23], v[208:211], v[166:169], v[20:23]
	v_mfma_f32_16x16x32_bf16 v[40:43], v[200:203], v[176:179], v[40:43]
	v_mfma_f32_16x16x32_bf16 v[8:11], v[208:211], v[176:179], v[8:11]
	v_mfma_f32_16x16x32_bf16 v[36:39], v[200:203], v[184:187], v[36:39]
	v_mfma_f32_16x16x32_bf16 v[0:3], v[208:211], v[184:187], v[0:3]
	v_mfma_f32_16x16x32_bf16 v[32:35], v[200:203], v[192:195], v[32:35]
	v_mfma_f32_16x16x32_bf16 v[4:7], v[208:211], v[192:195], v[4:7]
	v_mfma_f32_16x16x32_bf16 v[44:47], v[204:207], v[172:175], v[44:47]
	v_mfma_f32_16x16x32_bf16 v[20:23], v[212:215], v[172:175], v[20:23]
	v_mfma_f32_16x16x32_bf16 v[40:43], v[204:207], v[180:183], v[40:43]
	v_mfma_f32_16x16x32_bf16 v[8:11], v[212:215], v[180:183], v[8:11]
	v_mfma_f32_16x16x32_bf16 v[36:39], v[204:207], v[188:191], v[36:39]
	v_mfma_f32_16x16x32_bf16 v[0:3], v[212:215], v[188:191], v[0:3]
	v_mfma_f32_16x16x32_bf16 v[32:35], v[204:207], v[196:199], v[32:35]
	v_mfma_f32_16x16x32_bf16 v[4:7], v[212:215], v[196:199], v[4:7]
.Lp7_skipmma_7:
	s_setprio 0
	s_add_i32 s49, s49, 2
	s_add_u32 s11, s11, 0x100
	s_addc_u32 s33, s33, 0
	s_cmp_gt_u32 s49, 13
	s_mov_b64 s[12:13], s[68:69]
	s_barrier
; #define PG8_STAGE(bufoff, gbase, voff) do { _Pragma("unroll") for (int _i = 0; _i < 2; ++_i) \
;         __builtin_amdgcn_global_load_lds((const unsigned*)((const char*)(gbase) + (voff)[_i]), (LAS unsigned*)(lds + (bufoff) + ldsw + _i * 8192), 16, 0, 0); } while (0)
; #define PG8_LDA(dst, b, h) do { _Pragma("unroll") for (int m = 0; m < 4; ++m) _Pragma("unroll") for (int k = 0; k < 2; ++k) dst[m][k] = *(const LAS bf16x8*)(lds + PG8_SA(b, h) + aoff + m * 2048 + k * 1024); } while (0)
; #define PG8_LDB(dst, b, h) do { _Pragma("unroll") for (int n = 0; n < 2; ++n) _Pragma("unroll") for (int k = 0; k < 2; ++k) dst[n][k] = *(const LAS bf16x8*)(lds + PG8_SB(b, h) + boff + n * 2048 + k * 1024); } while (0)
; #define PG8_MMA(ai, bj, At, Bt) do { __builtin_amdgcn_s_setprio(1); _Pragma("unroll") for (int m = 0; m < 4; ++m) _Pragma("unroll") for (int n = 0; n < 2; ++n) _Pragma("unroll") for (int k = 0; k < 2; ++k) \
;         acc[ai][bj][m][n] = __builtin_amdgcn_mfma_f32_16x16x32_bf16(Bt[n][k], At[m][k], acc[ai][bj][m][n], 0, 0, 0); __builtin_amdgcn_s_setprio(0); } while (0)
; #define PG8_WAIT_L(n) asm volatile("s_waitcnt lgkmcnt(" #n ")" ::: "memory")
; #define PG8_BAR __builtin_amdgcn_s_barrier()
; #define PG8_SCHED __builtin_amdgcn_sched_barrier(0)
; template <class Epi, class Sched>
; __device__ __forceinline__ void gemm_phase(LAS unsigned char* lds, const int K, const Sched& S, const Epi& E) {
;     ...
;         for (int t = 0; t < nt; t += 2) {
;             const bool last = (t == nt - 2);
;             const char* a1 = cA + (size_t)(t + 1) * kstep;
;             const char* a2 = last ? nA : cA + (size_t)(t + 2) * kstep; const char* b2 = last ? nB : cB + (size_t)(t + 2) * kstep;
;             const char* a3 = a2 + kstep; const char* b3 = b2 + kstep;
;             PG8_LDB(B0, 0, 0); PG8_SCHED; PG8_LDA(At, 0, 0); PG8_STAGE(PG8_SA(1, 1), a1 + hstepA, voffA);
;             PG8_WAIT_L(8); PG8_BAR; PG8_WAIT_L(0); PG8_MMA(0, 0, At, B0); PG8_BAR; PG8_SCHED;
;             PG8_LDB(B1, 0, 1); PG8_STAGE(PG8_SB(0, 0), b2, voffB);
;             PG8_BAR; PG8_WAIT_L(0); PG8_MMA(0, 1, At, B1); PG8_BAR;
.LBB0_800:
	ds_read_b128 v[128:131], v158
	ds_read_b128 v[132:135], v158 offset:1024
	ds_read_b128 v[148:151], v158 offset:2048
	ds_read_b128 v[162:165], v158 offset:3072
	s_add_u32 s68, s12, 0x100
	s_addc_u32 s69, s13, 0
	s_cmp_eq_u32 s49, 12
	s_cselect_b32 s73, s63, s69
	s_cselect_b32 s72, s62, s68
	s_cselect_b32 s71, s65, s33
	s_cselect_b32 s70, s64, s11
	v_lshl_add_u64 v[200:201], s[12:13], 0, v[144:145]
	s_add_i32 m0, s67, 0xc000
	ds_read_b128 v[166:169], v159
	ds_read_b128 v[172:175], v159 offset:1024
	ds_read_b128 v[176:179], v159 offset:2048
	ds_read_b128 v[180:183], v159 offset:3072
	ds_read_b128 v[184:187], v159 offset:4096
	ds_read_b128 v[188:191], v159 offset:5120
	ds_read_b128 v[192:195], v159 offset:6144
	ds_read_b128 v[196:199], v159 offset:7168
	global_load_lds_dwordx4 v[200:201], off
	v_lshl_add_u64 v[200:201], s[12:13], 0, v[146:147]
	s_add_i32 m0, s67, 0xe000
	s_nop 0
	global_load_lds_dwordx4 v[200:201], off
	s_waitcnt lgkmcnt(8)
	s_barrier
	s_waitcnt lgkmcnt(0)
	s_setprio 1
	s_waitcnt lgkmcnt(0)
	s_cmp_eq_u32 s99, 0
	s_cbranch_scc1 .Lp7_skipmma_8
	v_mfma_f32_16x16x32_bf16 v[84:87], v[128:131], v[166:169], v[84:87]
	v_mfma_f32_16x16x32_bf16 v[76:79], v[148:151], v[166:169], v[76:79]
	v_mfma_f32_16x16x32_bf16 v[124:127], v[128:131], v[176:179], v[124:127]
	v_mfma_f32_16x16x32_bf16 v[72:75], v[148:151], v[176:179], v[72:75]
	v_mfma_f32_16x16x32_bf16 v[120:123], v[128:131], v[184:187], v[120:123]
	v_mfma_f32_16x16x32_bf16 v[96:99], v[148:151], v[184:187], v[96:99]
	v_mfma_f32_16x16x32_bf16 v[116:119], v[128:131], v[192:195], v[116:119]
	v_mfma_f32_16x16x32_bf16 v[92:95], v[148:151], v[192:195], v[92:95]
	v_mfma_f32_16x16x32_bf16 v[84:87], v[132:135], v[172:175], v[84:87]
	v_mfma_f32_16x16x32_bf16 v[76:79], v[162:165], v[172:175], v[76:79]
	v_mfma_f32_16x16x32_bf16 v[124:127], v[132:135], v[180:183], v[124:127]
	v_mfma_f32_16x16x32_bf16 v[72:75], v[162:165], v[180:183], v[72:75]
	v_mfma_f32_16x16x32_bf16 v[120:123], v[132:135], v[188:191], v[120:123]
	v_mfma_f32_16x16x32_bf16 v[96:99], v[162:165], v[188:191], v[96:99]
	v_mfma_f32_16x16x32_bf16 v[116:119], v[132:135], v[196:199], v[116:119]
	v_mfma_f32_16x16x32_bf16 v[92:95], v[162:165], v[196:199], v[92:95]
.Lp7_skipmma_8:
	s_setprio 0
	s_barrier
	s_add_i32 s12, s88, s78
	v_lshl_add_u64 v[216:217], s[70:71], 0, v[138:139]
	s_mov_b32 m0, s12
	ds_read_b128 v[200:203], v160
	ds_read_b128 v[204:207], v160 offset:1024
	ds_read_b128 v[208:211], v160 offset:2048
	ds_read_b128 v[212:215], v160 offset:3072
	global_load_lds_dwordx4 v[216:217], off
	v_lshl_add_u64 v[218:219], s[70:71], 0, v[142:143]
	s_add_i32 m0, s12, 0x2000
	s_nop 0
	global_load_lds_dwordx4 v[218:219], off
	s_barrier
	s_waitcnt lgkmcnt(0)
	s_setprio 1
	s_waitcnt lgkmcnt(0)
	s_cmp_eq_u32 s99, 0
	s_cbranch_scc1 .Lp7_skipmma_9
	v_mfma_f32_16x16x32_bf16 v[60:63], v[200:203], v[166:169], v[60:63]
	v_mfma_f32_16x16x32_bf16 v[16:19], v[208:211], v[166:169], v[16:19]
	v_mfma_f32_16x16x32_bf16 v[56:59], v[200:203], v[176:179], v[56:59]
	v_mfma_f32_16x16x32_bf16 v[12:15], v[208:211], v[176:179], v[12:15]
	v_mfma_f32_16x16x32_bf16 v[52:55], v[200:203], v[184:187], v[52:55]
	v_mfma_f32_16x16x32_bf16 v[28:31], v[208:211], v[184:187], v[28:31]
	v_mfma_f32_16x16x32_bf16 v[48:51], v[200:203], v[192:195], v[48:51]
	v_mfma_f32_16x16x32_bf16 v[24:27], v[208:211], v[192:195], v[24:27]
	v_mfma_f32_16x16x32_bf16 v[60:63], v[204:207], v[172:175], v[60:63]
	v_mfma_f32_16x16x32_bf16 v[16:19], v[212:215], v[172:175], v[16:19]
	v_mfma_f32_16x16x32_bf16 v[56:59], v[204:207], v[180:183], v[56:59]
	v_mfma_f32_16x16x32_bf16 v[12:15], v[212:215], v[180:183], v[12:15]
	v_mfma_f32_16x16x32_bf16 v[52:55], v[204:207], v[188:191], v[52:55]
	v_mfma_f32_16x16x32_bf16 v[28:31], v[212:215], v[188:191], v[28:31]
	v_mfma_f32_16x16x32_bf16 v[48:51], v[204:207], v[196:199], v[48:51]
	v_mfma_f32_16x16x32_bf16 v[24:27], v[212:215], v[196:199], v[24:27]
; #define PG8_STAGE(bufoff, gbase, voff) do { _Pragma("unroll") for (int _i = 0; _i < 2; ++_i) \
;         __builtin_amdgcn_global_load_lds((const unsigned*)((const char*)(gbase) + (voff)[_i]), (LAS unsigned*)(lds + (bufoff) + ldsw + _i * 8192), 16, 0, 0); } while (0)
; #define PG8_LDA(dst, b, h) do { _Pragma("unroll") for (int m = 0; m < 4; ++m) _Pragma("unroll") for (int k = 0; k < 2; ++k) dst[m][k] = *(const LAS bf16x8*)(lds + PG8_SA(b, h) + aoff + m * 2048 + k * 1024); } while (0)
; #define PG8_MMA(ai, bj, At, Bt) do { __builtin_amdgcn_s_setprio(1); _Pragma("unroll") for (int m = 0; m < 4; ++m) _Pragma("unroll") for (int n = 0; n < 2; ++n) _Pragma("unroll") for (int k = 0; k < 2; ++k) \
;         acc[ai][bj][m][n] = __builtin_amdgcn_mfma_f32_16x16x32_bf16(Bt[n][k], At[m][k], acc[ai][bj][m][n], 0, 0, 0); __builtin_amdgcn_s_setprio(0); } while (0)
; #define PG8_WAIT_V(n) asm volatile("s_waitcnt vmcnt(" #n ")" ::: "memory")
; #define PG8_WAIT_L(n) asm volatile("s_waitcnt lgkmcnt(" #n ")" ::: "memory")
; #define PG8_BAR __builtin_amdgcn_s_barrier()
; #define PG8_SCHED __builtin_amdgcn_sched_barrier(0)
; template <class Epi, class Sched>
; __device__ __forceinline__ void gemm_phase(LAS unsigned char* lds, const int K, const Sched& S, const Epi& E) {
;     ...
;             PG8_BAR; PG8_WAIT_L(0); PG8_MMA(0, 1, At, B1); PG8_BAR;
;             PG8_LDA(At, 0, 1); PG8_STAGE(PG8_SA(0, 0), a2, voffA);
;             PG8_BAR; PG8_WAIT_L(0); PG8_MMA(1, 0, At, B0); PG8_BAR; PG8_SCHED;
;             PG8_STAGE(PG8_SB(0, 1), b2 + hstep, voffB);
;             PG8_WAIT_V(6); PG8_BAR; PG8_MMA(1, 1, At, B1); PG8_BAR;
.Lp7_skipmma_9:
	s_setprio 0
	s_mov_b32 m0, s67
	v_lshl_add_u64 v[220:221], s[72:73], 0, v[136:137]
	s_barrier
	ds_read_b128 v[166:169], v159 offset:16384
	ds_read_b128 v[172:175], v159 offset:17408
	ds_read_b128 v[176:179], v159 offset:18432
	ds_read_b128 v[180:183], v159 offset:19456
	ds_read_b128 v[184:187], v159 offset:20480
	ds_read_b128 v[188:191], v159 offset:21504
	ds_read_b128 v[192:195], v159 offset:22528
	ds_read_b128 v[196:199], v159 offset:23552
	global_load_lds_dwordx4 v[220:221], off
	v_lshl_add_u64 v[222:223], s[72:73], 0, v[140:141]
	s_mov_b32 m0, s80
	s_nop 0
	global_load_lds_dwordx4 v[222:223], off
	s_barrier
	s_waitcnt lgkmcnt(0)
	s_setprio 1
	s_waitcnt lgkmcnt(0)
	s_cmp_eq_u32 s99, 0
	s_cbranch_scc1 .Lp7_skipmma_10
	v_mfma_f32_16x16x32_bf16 v[112:115], v[128:131], v[166:169], v[112:115]
	v_mfma_f32_16x16x32_bf16 v[88:91], v[148:151], v[166:169], v[88:91]
	v_mfma_f32_16x16x32_bf16 v[104:107], v[128:131], v[176:179], v[104:107]
	v_mfma_f32_16x16x32_bf16 v[80:83], v[148:151], v[176:179], v[80:83]
	v_mfma_f32_16x16x32_bf16 v[100:103], v[128:131], v[184:187], v[100:103]
	v_mfma_f32_16x16x32_bf16 v[64:67], v[148:151], v[184:187], v[64:67]
	v_mfma_f32_16x16x32_bf16 v[108:111], v[128:131], v[192:195], v[108:111]
	v_mfma_f32_16x16x32_bf16 v[68:71], v[148:151], v[192:195], v[68:71]
	v_mfma_f32_16x16x32_bf16 v[112:115], v[132:135], v[172:175], v[112:115]
	v_mfma_f32_16x16x32_bf16 v[88:91], v[162:165], v[172:175], v[88:91]
	v_mfma_f32_16x16x32_bf16 v[104:107], v[132:135], v[180:183], v[104:107]
	v_mfma_f32_16x16x32_bf16 v[80:83], v[162:165], v[180:183], v[80:83]
	v_mfma_f32_16x16x32_bf16 v[100:103], v[132:135], v[188:191], v[100:103]
	v_mfma_f32_16x16x32_bf16 v[64:67], v[162:165], v[188:191], v[64:67]
	v_mfma_f32_16x16x32_bf16 v[108:111], v[132:135], v[196:199], v[108:111]
	v_mfma_f32_16x16x32_bf16 v[68:71], v[162:165], v[196:199], v[68:71]
.Lp7_skipmma_10:
	s_setprio 0
	s_barrier
	s_add_u32 s12, s70, 0x40000
	s_addc_u32 s13, s71, 0
	s_add_i32 s52, s89, s78
	v_lshl_add_u64 v[128:129], s[12:13], 0, v[138:139]
	s_mov_b32 m0, s52
	s_nop 0
	global_load_lds_dwordx4 v[128:129], off
	v_lshl_add_u64 v[128:129], s[12:13], 0, v[142:143]
	s_add_i32 m0, s52, 0x2000
	s_nop 0
	global_load_lds_dwordx4 v[128:129], off
	s_waitcnt vmcnt(6)
	s_barrier
	s_setprio 1
	s_cmp_eq_u32 s99, 0
	s_cbranch_scc1 .Lp7_skipmma_11
	v_mfma_f32_16x16x32_bf16 v[44:47], v[200:203], v[166:169], v[44:47]
	v_mfma_f32_16x16x32_bf16 v[20:23], v[208:211], v[166:169], v[20:23]
	v_mfma_f32_16x16x32_bf16 v[40:43], v[200:203], v[176:179], v[40:43]
	v_mfma_f32_16x16x32_bf16 v[8:11], v[208:211], v[176:179], v[8:11]
	v_mfma_f32_16x16x32_bf16 v[36:39], v[200:203], v[184:187], v[36:39]
	v_mfma_f32_16x16x32_bf16 v[0:3], v[208:211], v[184:187], v[0:3]
	v_mfma_f32_16x16x32_bf16 v[32:35], v[200:203], v[192:195], v[32:35]
	v_mfma_f32_16x16x32_bf16 v[4:7], v[208:211], v[192:195], v[4:7]
	v_mfma_f32_16x16x32_bf16 v[44:47], v[204:207], v[172:175], v[44:47]
	v_mfma_f32_16x16x32_bf16 v[20:23], v[212:215], v[172:175], v[20:23]
	v_mfma_f32_16x16x32_bf16 v[40:43], v[204:207], v[180:183], v[40:43]
	v_mfma_f32_16x16x32_bf16 v[8:11], v[212:215], v[180:183], v[8:11]
	v_mfma_f32_16x16x32_bf16 v[36:39], v[204:207], v[188:191], v[36:39]
	v_mfma_f32_16x16x32_bf16 v[0:3], v[212:215], v[188:191], v[0:3]
	v_mfma_f32_16x16x32_bf16 v[32:35], v[204:207], v[196:199], v[32:35]
	v_mfma_f32_16x16x32_bf16 v[4:7], v[212:215], v[196:199], v[4:7]

; __device__ __forceinline__ unsigned cvt_pk_bf16(float lo, float hi) { unsigned r; asm volatile("v_cvt_pk_bf16_f32 %0, %1, %2" : "=v"(r) : "v"(lo), "v"(hi)); return r; }
; #define PG8_MMA(ai, bj, At, Bt) do { __builtin_amdgcn_s_setprio(1); _Pragma("unroll") for (int m = 0; m < 4; ++m) _Pragma("unroll") for (int n = 0; n < 2; ++n) _Pragma("unroll") for (int k = 0; k < 2; ++k) \
;         acc[ai][bj][m][n] = __builtin_amdgcn_mfma_f32_16x16x32_bf16(Bt[n][k], At[m][k], acc[ai][bj][m][n], 0, 0, 0); __builtin_amdgcn_s_setprio(0); } while (0)
; #define PG8_WAIT_V(n) asm volatile("s_waitcnt vmcnt(" #n ")" ::: "memory")
; #define PG8_BAR __builtin_amdgcn_s_barrier()
; template <class Epi, class Sched>
; __device__ __forceinline__ void gemm_phase(LAS unsigned char* lds, const int K, const Sched& S, const Epi& E) {
;     ...
;             PG8_WAIT_V(6); PG8_BAR; PG8_MMA(1, 1, At, B1); PG8_BAR;
;         }
;         if constexpr (!Epi::AFTER_DRAIN) E(acc, cur, wr, wc, fr, fq);
;         if (!has_next) break;
;     __device__ __forceinline__ void operator()(f32x4 (&acc)[2][2][4][2], const Unit& u, int wr, int wc, int fr, int fq) const {
;         const int J0 = u.pn * 128 + wc * 32 + fq * 8, sc = u.pm * 2 + wr;
;         const bool f0 = (fr == 0), f15 = (fr == 15);
;         if (f0 || f15) {
; #pragma unroll
;             for (int bj = 0; bj < 2; ++bj)
; #pragma unroll
;                 for (int q = 0; q < 2; ++q) { const f32x4 a0 = f0 ? acc[0][bj][q][0] : acc[1][bj][2 + q][0], a1 = f0 ? acc[0][bj][q][1] : acc[1][bj][2 + q][1];
;                     u32x4 w; w.x = cvt_pk_bf16(a0[0], a0[1]); w.y = cvt_pk_bf16(a0[2], a0[3]); w.z = cvt_pk_bf16(a1[0], a1[1]); w.w = cvt_pk_bf16(a1[2], a1[3]);
;                     *(u32x4*)(side + (size_t)(sc * 4 + (f0 ? q : 2 + q)) * (2 * DFF) + bj * DFF + J0) = w; }
.Lp7_skipmma_15:
	s_setprio 0
	s_add_i32 s49, s49, 2
	s_add_u32 s11, s11, 0x100
	s_addc_u32 s33, s33, 0
	s_cmp_gt_u32 s49, 13
	s_mov_b64 s[12:13], s[68:69]
	s_barrier
	s_cbranch_scc0 .LBB0_800
	s_cmp_eq_u32 s99, 0
	s_cbranch_scc0 .Lp7_do_epi
	s_mov_b64 s[12:13], exec
	s_branch .LBB0_796
.Lp7_do_epi:
	v_lshl_or_b32 v150, s10, 7, v157
	v_add_u32_e32 v254, 0x2c00, v253
	global_load_dwordx4 v[208:211], v253, s[22:23] offset:16
	global_load_dwordx4 v[212:215], v253, s[24:25] offset:16
	global_load_dwordx4 v[216:219], v253, s[26:27] offset:16
	global_load_dwordx4 v[220:223], v253, s[36:37] offset:16
	v_cmp_gt_i32_e32 vcc, 15, v152
	s_mov_b64 s[70:71], -1
	s_and_saveexec_b64 s[68:69], vcc
	s_cbranch_execz .LBB0_805
	v_cmp_eq_u32_e32 vcc, 0, v152
	v_cmp_ne_u32_e64 s[12:13], 0, v152
	s_and_saveexec_b64 s[70:71], s[12:13]
	v_ashrrev_i32_e32 v151, 31, v150
	v_mov_b64_e32 v[148:149], v[150:151]
	s_or_b64 exec, exec, s[70:71]
	s_orn2_b64 s[70:71], vcc, exec
